# P0 weight (w_in/w_out) transposition rewritten by hand like the FFN one: all 10 loads in flight, no per-element gain round trips, no LDS
# speedup vs baseline: 1.0714x; 1.0386x over previous
; #define LAS __attribute__((address_space(3)))
; DI unsigned pk(float a, float b) { f32x2 v = {a, b}; bf16x2_t r = __builtin_convertvector(v, bf16x2_t); return __builtin_bit_cast(unsigned, r); }
; DI int win_perm(int n) {
;     if (n >= 768 && n < 1792) { const int r = n & 255, hl = r >> 7, half = (r >> 6) & 1, q = (r >> 5) & 1; return (n & ~255) + 64 * (2 * hl + q) + 32 * half + (r & 31); }
;     return n;
; }
; DI void p0_transpose_item(const float* W, int K, int N, bf16_t* WT, const float* gain, bool is_win, LAS float* scr, int item, int lane) {
;     const int nblk = N / 32, kb = item / nblk, nb = item % nblk, k0 = 64 * kb, n0 = 32 * nb;
;     float cs = 1.f; int prow = n0;
;     if (is_win) { prow = win_perm(n0); if (n0 < 512) cs = 0.125f; else if (n0 >= 1280 && n0 < 1792) cs = 0.08838834764831845f; }
; #pragma unroll 8
;     for (int i = 0; i < 32; ++i) { const int kk = 2 * i + (lane >> 5); float w = __builtin_nontemporal_load(W + (size_t)(k0 + kk) * N + n0 + (lane & 31)) * cs;     if (gain) w *= gain[k0 + kk]; scr[kk * 33 + (lane & 31)] = w; }
;     asm volatile("s_waitcnt lgkmcnt(0)" ::: "memory");
;     const int c = lane & 7;
; #pragma unroll
;     for (int j = 0; j < 4; ++j) { const int n = (lane >> 3) + 8 * j; const LAS float* s = scr + (8 * c) * 33 + n;
;         u32x4 o; o.x = pk(s[0 * 33], s[1 * 33]); o.y = pk(s[2 * 33], s[3 * 33]); o.z = pk(s[4 * 33], s[5 * 33]); o.w = pk(s[6 * 33], s[7 * 33]);
;         *(u32x4*)(WT + (size_t)(prow + n) * K + k0 + 8 * c) = o; }
; DI void p0_prologue(const Params& P, lds_t* lds, int G, int tid, int wave, int lane, bool late_ffn) {
;     ...
;     for (int it = gw; it < n_items; it += NGW) {
;         int r = it;
;         if (r < I_IN) { p0_transpose_item(P.w_in, DM, INW, (bf16_t*)(ws + WS_WIN), P.norm1, true, scr, r, lane); continue; } r -= I_IN;
;         if (r < I_OUT) { p0_transpose_item(P.w_out, DM, DM, (bf16_t*)(ws + WS_WOUT), nullptr, false, scr, r, lane); continue; } r -= I_OUT;
.LBB0_5:
	s_or_b64 exec, exec, s[4:5]
	s_load_dwordx16 s[36:51], s[0:1], 0x0
	v_readlane_b32 s1, v255, 10
	v_mbcnt_lo_u32_b32 v0, -1, 0
	s_and_b32 s97, s1, 0xffffffc0
	v_mbcnt_hi_u32_b32 v201, -1, v0
	s_lshr_b32 s0, s1, 6
	v_add_u32_e32 v175, s97, v201
	s_lshl_b32 s1, s2, 3
	v_mov_b32_e32 v28, v175
	v_writelane_b32 v255, s0, 13
	s_add_i32 s64, s0, s1
	s_lshl_b32 s66, s96, 3
	s_mov_b32 s5, 0
	v_writelane_b32 v255, s1, 14
	s_cmpk_gt_i32 s64, 0x77f
	v_and_b32_e32 v1, 63, v28
	s_cbranch_scc1 .LBB0_32
	s_waitcnt lgkmcnt(0)
	v_and_b32_e32 v123, 7, v201
	v_lshrrev_b32_e32 v122, 3, v201
	v_lshlrev_b32_e32 v124, 5, v122
	s_cmpk_lt_u32 s64, 0x580
	s_cbranch_scc0 .Lp0w_wout
	s_mul_i32 s0, s64, 0x2e9
	s_lshr_b32 s0, s0, 16
	s_mul_i32 s1, s0, 0x58
	s_sub_u32 s1, s64, s1
	s_lshl_b32 s3, s1, 5
	s_mov_b32 s15, 1.0
	s_cmpk_lt_u32 s3, 0x200
	s_cselect_b32 s15, 0x3e000000, s15
	s_sub_u32 s4, s3, 0x500
	s_cmpk_lt_u32 s4, 0x200
	s_cselect_b32 s15, 0x3db504f3, s15
	s_and_b32 s17, s3, 0xff
	s_lshr_b32 s18, s17, 7
	s_lshl_b32 s18, s18, 7
	s_bfe_u32 s19, s17, 0x10005
	s_lshl_b32 s19, s19, 6
	s_add_u32 s18, s18, s19
	s_bfe_u32 s19, s17, 0x10006
	s_lshl_b32 s19, s19, 5
	s_add_u32 s18, s18, s19
	s_andn2_b32 s19, s3, 0xff
	s_add_u32 s18, s18, s19
	s_sub_u32 s4, s3, 0x300
	s_cmpk_lt_u32 s4, 0x400
	s_cselect_b32 s3, s18, s3
	s_mul_i32 s4, s0, 0xb0000
	s_lshl_b32 s17, s1, 7
	s_add_u32 s4, s4, s17
	s_add_u32 s6, s48, s4
	s_addc_u32 s7, s49, 0
	s_lshl_b32 s4, s3, 11
	s_lshl_b32 s17, s0, 7
	s_add_u32 s4, s4, s17
	s_add_u32 s4, s4, 0x200000
	s_add_u32 s8, s68, s4
	s_addc_u32 s9, s69, 0
	s_movk_i32 s12, 0x2c00
	s_mov_b32 s14, 1
	s_branch .Lp0w_common
.Lp0w_wout:
	s_sub_u32 s4, s64, 0x580
	s_lshr_b32 s0, s4, 5
	s_and_b32 s1, s4, 31
	v_readlane_b32 s6, v255, 0
	v_readlane_b32 s7, v255, 1
	s_lshl_b32 s4, s0, 18
	s_lshl_b32 s17, s1, 7
	s_add_u32 s4, s4, s17
	s_add_u32 s6, s6, s4
	s_addc_u32 s7, s7, 0
	s_lshl_b32 s4, s1, 16
	s_lshl_b32 s17, s0, 7
	s_add_u32 s4, s4, s17
	s_add_u32 s4, s4, 0x800000
	s_add_u32 s8, s68, s4
	s_addc_u32 s9, s69, 0
	s_movk_i32 s12, 0x1000
	s_mov_b32 s14, 0
	s_mov_b32 s15, 1.0
	s_and_b32 s0, s0, 15
.Lp0w_common:
	s_lshl_b32 s0, s0, 8
	s_add_u32 s10, s46, s0
	s_addc_u32 s11, s47, 0
	s_lshl_b32 s0, s12, 3
	v_lshlrev_b32_e32 v120, 4, v123
	v_mad_u32_u24 v120, v122, s0, v120
	v_lshlrev_b32_e32 v121, 13, v123
	v_lshl_add_u32 v121, v122, 4, v121
	s_nop 1
	global_load_dwordx4 v[64:67], v120, s[6:7] nt
	v_add_u32_e32 v120, s12, v120
	global_load_dwordx4 v[68:71], v120, s[6:7] nt
	v_add_u32_e32 v120, s12, v120
	global_load_dwordx4 v[72:75], v120, s[6:7] nt
	v_add_u32_e32 v120, s12, v120
	global_load_dwordx4 v[76:79], v120, s[6:7] nt
	v_add_u32_e32 v120, s12, v120
	global_load_dwordx4 v[80:83], v120, s[6:7] nt
	v_add_u32_e32 v120, s12, v120
	global_load_dwordx4 v[84:87], v120, s[6:7] nt
	v_add_u32_e32 v120, s12, v120
	global_load_dwordx4 v[88:91], v120, s[6:7] nt
	v_add_u32_e32 v120, s12, v120
	global_load_dwordx4 v[92:95], v120, s[6:7] nt
	global_load_dwordx4 v[96:99], v124, s[10:11]
	global_load_dwordx4 v[100:103], v124, s[10:11] offset:16
	s_waitcnt vmcnt(0)
	s_cmp_eq_u32 s15, 1.0
	s_cbranch_scc1 .Lp0w_nocs
	v_mul_f32_e32 v64, s15, v64
	v_mul_f32_e32 v65, s15, v65
	v_mul_f32_e32 v66, s15, v66
	v_mul_f32_e32 v67, s15, v67
	v_mul_f32_e32 v68, s15, v68
	v_mul_f32_e32 v69, s15, v69
	v_mul_f32_e32 v70, s15, v70
	v_mul_f32_e32 v71, s15, v71
	v_mul_f32_e32 v72, s15, v72
	v_mul_f32_e32 v73, s15, v73
	v_mul_f32_e32 v74, s15, v74
	v_mul_f32_e32 v75, s15, v75
	v_mul_f32_e32 v76, s15, v76
	v_mul_f32_e32 v77, s15, v77
	v_mul_f32_e32 v78, s15, v78
	v_mul_f32_e32 v79, s15, v79
	v_mul_f32_e32 v80, s15, v80
	v_mul_f32_e32 v81, s15, v81
	v_mul_f32_e32 v82, s15, v82
	v_mul_f32_e32 v83, s15, v83
	v_mul_f32_e32 v84, s15, v84
	v_mul_f32_e32 v85, s15, v85
	v_mul_f32_e32 v86, s15, v86
	v_mul_f32_e32 v87, s15, v87
	v_mul_f32_e32 v88, s15, v88
	v_mul_f32_e32 v89, s15, v89
	v_mul_f32_e32 v90, s15, v90
	v_mul_f32_e32 v91, s15, v91
	v_mul_f32_e32 v92, s15, v92
	v_mul_f32_e32 v93, s15, v93
	v_mul_f32_e32 v94, s15, v94
	v_mul_f32_e32 v95, s15, v95
.Lp0w_nocs:
	s_cmp_eq_u32 s14, 0
	s_cbranch_scc1 .Lp0w_nog
	v_mul_f32_e32 v64, v64, v96
	v_mul_f32_e32 v65, v65, v96
	v_mul_f32_e32 v66, v66, v96
	v_mul_f32_e32 v67, v67, v96
	v_mul_f32_e32 v68, v68, v97
	v_mul_f32_e32 v69, v69, v97
	v_mul_f32_e32 v70, v70, v97
	v_mul_f32_e32 v71, v71, v97
	v_mul_f32_e32 v72, v72, v98
	v_mul_f32_e32 v73, v73, v98
	v_mul_f32_e32 v74, v74, v98
	v_mul_f32_e32 v75, v75, v98
	v_mul_f32_e32 v76, v76, v99
	v_mul_f32_e32 v77, v77, v99
	v_mul_f32_e32 v78, v78, v99
	v_mul_f32_e32 v79, v79, v99
	v_mul_f32_e32 v80, v80, v100
	v_mul_f32_e32 v81, v81, v100
	v_mul_f32_e32 v82, v82, v100
	v_mul_f32_e32 v83, v83, v100
	v_mul_f32_e32 v84, v84, v101
	v_mul_f32_e32 v85, v85, v101
	v_mul_f32_e32 v86, v86, v101
	v_mul_f32_e32 v87, v87, v101
	v_mul_f32_e32 v88, v88, v102
	v_mul_f32_e32 v89, v89, v102
	v_mul_f32_e32 v90, v90, v102
	v_mul_f32_e32 v91, v91, v102
	v_mul_f32_e32 v92, v92, v103
	v_mul_f32_e32 v93, v93, v103
	v_mul_f32_e32 v94, v94, v103
	v_mul_f32_e32 v95, v95, v103
.Lp0w_nog:
	v_cvt_pk_bf16_f32 v104, v64, v68
	v_cvt_pk_bf16_f32 v105, v72, v76
	v_cvt_pk_bf16_f32 v106, v80, v84
	v_cvt_pk_bf16_f32 v107, v88, v92
	global_store_dwordx4 v121, v[104:107], s[8:9]
	v_add_u32_e32 v121, 0x800, v121
	v_cvt_pk_bf16_f32 v108, v65, v69
	v_cvt_pk_bf16_f32 v109, v73, v77
	v_cvt_pk_bf16_f32 v110, v81, v85
	v_cvt_pk_bf16_f32 v111, v89, v93
	global_store_dwordx4 v121, v[108:111], s[8:9]
	v_add_u32_e32 v121, 0x800, v121
	v_cvt_pk_bf16_f32 v112, v66, v70
	v_cvt_pk_bf16_f32 v113, v74, v78
	v_cvt_pk_bf16_f32 v114, v82, v86
	v_cvt_pk_bf16_f32 v115, v90, v94
	global_store_dwordx4 v121, v[112:115], s[8:9]
	v_add_u32_e32 v121, 0x800, v121
	v_cvt_pk_bf16_f32 v116, v67, v71
	v_cvt_pk_bf16_f32 v117, v75, v79
	v_cvt_pk_bf16_f32 v118, v83, v87
	v_cvt_pk_bf16_f32 v119, v91, v95
	global_store_dwordx4 v121, v[116:119], s[8:9]
